# scan->gate XCD-local seam waits for the gdn_pre of the one batch whose q|k|v input its gated rows overwrite (per-batch word, counted after the pre->scan seam); launch-wide scan count is posted after t
# speedup vs baseline: 1.0074x; 1.0074x over previous
.Lfb_done_1:
	s_waitcnt vmcnt(0) lgkmcnt(0)
	s_and_b32 s9, s2, 7
	s_lshl_b32 s9, s9, 8
	s_add_u32 s9, s9, 0x3648
	v_mov_b32_e32 v6, s9
	v_mov_b32_e32 v7, 1
	global_atomic_add v6, v7, s[4:5]
	s_branch .LBB0_361

.Lscan_loop:
	s_and_b32 s7, s6, 3
	s_lshl_b32 s7, s7, 12
	v_add_u32_e32 v23, s7, v22
	ds_read_b128 v[32:35], v10 offset:0
	ds_read_b128 v[48:51], v11 offset:0
	ds_read_b128 v[36:39], v10 offset:64
	ds_read_b128 v[52:55], v12 offset:0
	ds_read_b128 v[40:43], v10 offset:128
	ds_read_b128 v[56:59], v13 offset:0
	ds_read_b128 v[44:47], v10 offset:192
	ds_read_b128 v[60:63], v14 offset:0
	ds_read_u16 v80, v23 offset:0
	ds_read_u16 v81, v23 offset:64
	ds_read_u16 v82, v23 offset:128
	ds_read_u16 v83, v23 offset:192
	s_add_u32 s33, s6, 1
	s_min_u32 s33, s33, 31
	s_add_u32 s36, s6, 2
	s_min_u32 s36, s36, 31
	v_readlane_b32 s37, v24, s6
	s_nop 1
	v_mul_f32_e32 v92, s37, v92
	v_mul_f32_e32 v93, s37, v93
	v_mul_f32_e32 v94, s37, v94
	v_mul_f32_e32 v95, s37, v95
	v_mul_f32_e32 v96, s37, v96
	v_mul_f32_e32 v97, s37, v97
	v_mul_f32_e32 v98, s37, v98
	v_mul_f32_e32 v99, s37, v99
	s_waitcnt lgkmcnt(10)
	v_mfma_f32_16x16x32_bf16 v[84:87], v[48:51], v[32:35], 0
	s_waitcnt lgkmcnt(8)
	v_mfma_f32_16x16x32_bf16 v[84:87], v[52:55], v[36:39], v[84:87]
	s_waitcnt lgkmcnt(6)
	v_mfma_f32_16x16x32_bf16 v[84:87], v[56:59], v[40:43], v[84:87]
	s_waitcnt lgkmcnt(4)
	v_mfma_f32_16x16x32_bf16 v[84:87], v[60:63], v[44:47], v[84:87]
	ds_read_b128 v[64:67], v11 offset:32768
	ds_read_b128 v[68:71], v12 offset:32768
	ds_read_b128 v[72:75], v13 offset:32768
	ds_read_b128 v[76:79], v14 offset:32768
	s_waitcnt lgkmcnt(4)
	v_lshlrev_b32_e32 v80, 16, v80
	v_lshlrev_b32_e32 v81, 16, v81
	v_lshlrev_b32_e32 v82, 16, v82
	v_lshlrev_b32_e32 v83, 16, v83
	v_sub_f32_e32 v26, v80, v84
	v_sub_f32_e32 v27, v81, v85
	v_sub_f32_e32 v28, v82, v86
	v_sub_f32_e32 v29, v83, v87
	v_cvt_pk_bf16_f32 v26, v26, v27
	v_cvt_pk_bf16_f32 v27, v28, v29
	ds_write_b64 v20, v[26:27]
	s_lshl_b32 s7, s33, 14
	s_add_u32 s26, s14, s7
	s_addc_u32 s27, s15, 0
	s_add_i32 m0, s30, 0x14000
	s_nop 0
	global_load_lds_dwordx4 v5, s[26:27]
	s_add_i32 m0, s30, 0x14400
	s_nop 0
	global_load_lds_dwordx4 v6, s[26:27]
	s_lshl_b32 s7, s33, 13
	s_add_u32 s28, s18, s7
	s_addc_u32 s29, s19, 0
	s_add_i32 m0, s31, 0x1a000
	s_nop 0
	global_load_lds_dwordx4 v7, s[28:29]
	s_lshl_b32 s7, s36, 14
	s_add_u32 s26, s24, s7
	s_addc_u32 s27, s25, 0
	s_add_u32 s8, s6, 2
	s_and_b32 s8, s8, 3
	s_lshl_b32 s8, s8, 12
	s_add_u32 s8, s8, s32
	s_add_i32 m0, s8, 0x1f400
	s_nop 0
	global_load_lds_dwordx4 v8, s[26:27]
	s_waitcnt vmcnt(10) lgkmcnt(0)
	s_barrier
	ds_read_b128 v[100:103], v19
	ds_read_b128 v[108:111], v15 offset:0
	ds_read_b128 v[112:115], v15 offset:2048
	ds_read_b128 v[104:107], v19 offset:64
	ds_read_b128 v[116:119], v16 offset:0
	ds_read_b128 v[120:123], v16 offset:2048
	ds_read_b128 v[124:127], v17 offset:0
	ds_read_b128 v[128:131], v18 offset:0
	v_mfma_f32_16x16x32_bf16 v[88:91], v[32:35], v[64:67], 0
	v_mfma_f32_16x16x32_bf16 v[88:91], v[36:39], v[68:71], v[88:91]
	v_mfma_f32_16x16x32_bf16 v[88:91], v[40:43], v[72:75], v[88:91]
	v_mfma_f32_16x16x32_bf16 v[88:91], v[44:47], v[76:79], v[88:91]
	s_waitcnt lgkmcnt(6)
	v_mfma_f32_16x16x32_bf16 v[92:95], v[108:111], v[100:103], v[92:95]
	s_waitcnt lgkmcnt(5)
	v_mfma_f32_16x16x32_bf16 v[96:99], v[112:115], v[100:103], v[96:99]
	s_waitcnt lgkmcnt(3)
	v_mfma_f32_16x16x32_bf16 v[92:95], v[116:119], v[104:107], v[92:95]
	s_waitcnt lgkmcnt(2)
	v_mfma_f32_16x16x32_bf16 v[96:99], v[120:123], v[104:107], v[96:99]
	s_waitcnt lgkmcnt(1)
	v_mfma_f32_16x16x32_bf16 v[88:91], v[100:103], v[124:127], v[88:91]
	s_waitcnt lgkmcnt(0)
	v_mfma_f32_16x16x32_bf16 v[88:91], v[104:107], v[128:131], v[88:91]
	s_lshl_b32 s7, s6, 14
	s_add_u32 s28, s24, s7
	s_addc_u32 s29, s25, 0
	s_nop 1
	v_cvt_pk_bf16_f32 v26, v92, v93
	v_cvt_pk_bf16_f32 v27, v94, v95
	v_cvt_pk_bf16_f32 v28, v96, v97
	v_cvt_pk_bf16_f32 v29, v98, v99
	ds_write_b64 v21, v[26:27]
	ds_write_b64 v21, v[28:29] offset:32
	s_lshl_b32 s7, s36, 14
	s_add_u32 s26, s10, s7
	s_addc_u32 s27, s11, 0
	s_add_i32 m0, s30, 0x0
	s_nop 0
	global_load_lds_dwordx4 v3, s[26:27]
	s_add_i32 m0, s30, 0x400
	s_nop 0
	global_load_lds_dwordx4 v4, s[26:27]
	s_lshl_b32 s7, s36, 14
	s_add_u32 s26, s12, s7
	s_addc_u32 s27, s13, 0
	s_add_i32 m0, s30, 0x8000
	s_nop 0
	global_load_lds_dwordx4 v3, s[26:27]
	s_add_i32 m0, s30, 0x8400
	s_nop 0
	global_load_lds_dwordx4 v4, s[26:27]
	v_cvt_pk_bf16_f32 v80, v88, v89
	v_cvt_pk_bf16_f32 v81, v90, v91
	global_store_dwordx2 v9, v[80:81], s[28:29]
	s_add_u32 s6, s6, 1
	s_waitcnt vmcnt(10) lgkmcnt(0)
	s_barrier
	s_and_b32 s7, s6, 3
	s_lshl_b32 s7, s7, 12
	v_add_u32_e32 v23, s7, v22
	ds_read_b128 v[32:35], v10 offset:0
	ds_read_b128 v[48:51], v11 offset:16384
	ds_read_b128 v[36:39], v10 offset:64
	ds_read_b128 v[52:55], v12 offset:16384
	ds_read_b128 v[40:43], v10 offset:128
	ds_read_b128 v[56:59], v13 offset:16384
	ds_read_b128 v[44:47], v10 offset:192
	ds_read_b128 v[60:63], v14 offset:16384
	ds_read_u16 v80, v23 offset:0
	ds_read_u16 v81, v23 offset:64
	ds_read_u16 v82, v23 offset:128
	ds_read_u16 v83, v23 offset:192
	s_add_u32 s33, s6, 1
	s_min_u32 s33, s33, 31
	s_add_u32 s36, s6, 2
	s_min_u32 s36, s36, 31
	v_readlane_b32 s37, v24, s6
	s_nop 1
	v_mul_f32_e32 v92, s37, v92
	v_mul_f32_e32 v93, s37, v93
	v_mul_f32_e32 v94, s37, v94
	v_mul_f32_e32 v95, s37, v95
	v_mul_f32_e32 v96, s37, v96
	v_mul_f32_e32 v97, s37, v97
	v_mul_f32_e32 v98, s37, v98
	v_mul_f32_e32 v99, s37, v99
	s_waitcnt lgkmcnt(10)
	v_mfma_f32_16x16x32_bf16 v[84:87], v[48:51], v[32:35], 0
	s_waitcnt lgkmcnt(8)
	v_mfma_f32_16x16x32_bf16 v[84:87], v[52:55], v[36:39], v[84:87]
	s_waitcnt lgkmcnt(6)
	v_mfma_f32_16x16x32_bf16 v[84:87], v[56:59], v[40:43], v[84:87]
	s_waitcnt lgkmcnt(4)
	v_mfma_f32_16x16x32_bf16 v[84:87], v[60:63], v[44:47], v[84:87]
	ds_read_b128 v[64:67], v11 offset:49152
	ds_read_b128 v[68:71], v12 offset:49152
	ds_read_b128 v[72:75], v13 offset:49152
	ds_read_b128 v[76:79], v14 offset:49152
	s_waitcnt lgkmcnt(4)
	v_lshlrev_b32_e32 v80, 16, v80
	v_lshlrev_b32_e32 v81, 16, v81
	v_lshlrev_b32_e32 v82, 16, v82
	v_lshlrev_b32_e32 v83, 16, v83
	v_sub_f32_e32 v26, v80, v84
	v_sub_f32_e32 v27, v81, v85
	v_sub_f32_e32 v28, v82, v86
	v_sub_f32_e32 v29, v83, v87
	v_cvt_pk_bf16_f32 v26, v26, v27
	v_cvt_pk_bf16_f32 v27, v28, v29
	ds_write_b64 v20, v[26:27]
	s_lshl_b32 s7, s33, 14
	s_add_u32 s26, s14, s7
	s_addc_u32 s27, s15, 0
	s_add_i32 m0, s30, 0x10000
	s_nop 0
	global_load_lds_dwordx4 v5, s[26:27]
	s_add_i32 m0, s30, 0x10400
	s_nop 0
	global_load_lds_dwordx4 v6, s[26:27]
	s_lshl_b32 s7, s33, 13
	s_add_u32 s28, s18, s7
	s_addc_u32 s29, s19, 0
	s_add_i32 m0, s31, 0x18000
	s_nop 0
	global_load_lds_dwordx4 v7, s[28:29]
	s_lshl_b32 s7, s36, 14
	s_add_u32 s26, s24, s7
	s_addc_u32 s27, s25, 0
	s_add_u32 s8, s6, 2
	s_and_b32 s8, s8, 3
	s_lshl_b32 s8, s8, 12
	s_add_u32 s8, s8, s32
	s_add_i32 m0, s8, 0x1f400
	s_nop 0
	global_load_lds_dwordx4 v8, s[26:27]
	s_waitcnt vmcnt(10) lgkmcnt(0)
	s_barrier
	ds_read_b128 v[100:103], v19
	ds_read_b128 v[108:111], v15 offset:16384
	ds_read_b128 v[112:115], v15 offset:18432
	ds_read_b128 v[104:107], v19 offset:64
	ds_read_b128 v[116:119], v16 offset:16384
	ds_read_b128 v[120:123], v16 offset:18432
	ds_read_b128 v[124:127], v17 offset:8192
	ds_read_b128 v[128:131], v18 offset:8192
	v_mfma_f32_16x16x32_bf16 v[88:91], v[32:35], v[64:67], 0
	v_mfma_f32_16x16x32_bf16 v[88:91], v[36:39], v[68:71], v[88:91]
	v_mfma_f32_16x16x32_bf16 v[88:91], v[40:43], v[72:75], v[88:91]
	v_mfma_f32_16x16x32_bf16 v[88:91], v[44:47], v[76:79], v[88:91]
	s_waitcnt lgkmcnt(6)
	v_mfma_f32_16x16x32_bf16 v[92:95], v[108:111], v[100:103], v[92:95]
	s_waitcnt lgkmcnt(5)
	v_mfma_f32_16x16x32_bf16 v[96:99], v[112:115], v[100:103], v[96:99]
	s_waitcnt lgkmcnt(3)
	v_mfma_f32_16x16x32_bf16 v[92:95], v[116:119], v[104:107], v[92:95]
	s_waitcnt lgkmcnt(2)
	v_mfma_f32_16x16x32_bf16 v[96:99], v[120:123], v[104:107], v[96:99]
	s_waitcnt lgkmcnt(1)
	v_mfma_f32_16x16x32_bf16 v[88:91], v[100:103], v[124:127], v[88:91]
	s_waitcnt lgkmcnt(0)
	v_mfma_f32_16x16x32_bf16 v[88:91], v[104:107], v[128:131], v[88:91]
	s_lshl_b32 s7, s6, 14
	s_add_u32 s28, s24, s7
	s_addc_u32 s29, s25, 0
	s_nop 1
	v_cvt_pk_bf16_f32 v26, v92, v93
	v_cvt_pk_bf16_f32 v27, v94, v95
	v_cvt_pk_bf16_f32 v28, v96, v97
	v_cvt_pk_bf16_f32 v29, v98, v99
	ds_write_b64 v21, v[26:27]
	ds_write_b64 v21, v[28:29] offset:32
	s_lshl_b32 s7, s36, 14
	s_add_u32 s26, s10, s7
	s_addc_u32 s27, s11, 0
	s_add_i32 m0, s30, 0x4000
	s_nop 0
	global_load_lds_dwordx4 v3, s[26:27]
	s_add_i32 m0, s30, 0x4400
	s_nop 0
	global_load_lds_dwordx4 v4, s[26:27]
	s_lshl_b32 s7, s36, 14
	s_add_u32 s26, s12, s7
	s_addc_u32 s27, s13, 0
	s_add_i32 m0, s30, 0xc000
	s_nop 0
	global_load_lds_dwordx4 v3, s[26:27]
	s_add_i32 m0, s30, 0xc400
	s_nop 0
	global_load_lds_dwordx4 v4, s[26:27]
	v_cvt_pk_bf16_f32 v80, v88, v89
	v_cvt_pk_bf16_f32 v81, v90, v91
	global_store_dwordx2 v9, v[80:81], s[28:29]
	s_add_u32 s6, s6, 1
	s_waitcnt vmcnt(10) lgkmcnt(0)
	s_barrier
	s_cmp_lt_u32 s6, 32
	s_cbranch_scc1 .Lscan_loop
	s_lshl_b32 s56, s77, 5
	s_and_b32 s57, s40, 3
	s_lshl_b32 s72, s40, 5
	s_waitcnt vmcnt(0)
	v_readfirstlane_b32 s3, v194
	s_cmp_gt_u32 s3, 63
	s_barrier
	s_cbranch_scc1 .LBB0_421
	s_waitcnt vmcnt(2)
	v_mbcnt_lo_u32_b32 v0, -1, 0
	v_mbcnt_hi_u32_b32 v0, -1, v0
	s_nop 0
	v_cmp_eq_u32_e32 vcc, 0, v0
	s_and_saveexec_b64 s[6:7], vcc
	s_cbranch_execz .LBB0_420
	v_mov_b32_e32 v0, 0x23ff0
	s_waitcnt vmcnt(0) lgkmcnt(0)
	ds_read_b128 v[0:3], v0
	s_waitcnt lgkmcnt(0)
	v_readfirstlane_b32 s3, v2
	s_nop 0
	s_cmp_eq_u32 s3, 0
	s_cbranch_scc1 .Lfb_slow_2
	v_readfirstlane_b32 s8, v0
	s_cmp_eq_u32 s8, 32
	s_cbranch_scc0 .Lfb_xcd_2
	buffer_inv sc1
	s_getreg_b32 s3, hwreg(HW_REG_XCC_ID, 0, 4)
	s_and_b32 s3, s3, 7
	s_lshl_b32 s3, s3, 8
	s_add_u32 s3, s3, 0x3600
	s_add_u32 s4, s92, 0x510000
	s_addc_u32 s5, s93, 0
	v_mov_b32_e32 v7, 1
	s_mov_b32 s8, s3
	s_add_u32 s8, s8, 0x5c
	v_mov_b32_e32 v6, s8
	global_atomic_add v6, v7, s[4:5]
	s_mov_b32 s8, s3
	s_add_u32 s8, s8, 0x5c
	v_mov_b32_e32 v6, s8
	s_and_b32 s8, s2, 7
	s_mul_i32 s8, s8, 11
	s_lshr_b32 s8, s8, 5
	s_lshl_b32 s8, s8, 8
	s_add_u32 s8, s8, 0x3648
	v_mov_b32_e32 v4, s8
	s_mov_b32 s8, 0
.Lfb_gs_2:
	global_load_dword v8, v6, s[4:5] sc1
	global_load_dword v5, v4, s[4:5] sc1
	s_waitcnt vmcnt(0)
	v_add_u32_e32 v8, -32, v8
	v_add_u32_e32 v5, -32, v5
	v_min_i32_e32 v8, v8, v5
	v_cmp_le_i32_e32 vcc, 0, v8
	s_cbranch_vccnz .Lfb_done_2
	s_sleep 1
	s_add_u32 s8, s8, 1
	s_cmp_lt_u32 s8, 0x40000
	s_cbranch_scc1 .Lfb_gs_2
	s_branch .Lfb_done_2
.Lfb_xcd_2:
	s_add_u32 s4, s92, 0x510000
	s_addc_u32 s5, s93, 0
	s_and_b32 s8, s2, 7
	s_mul_i32 s8, s8, 11
	s_lshr_b32 s8, s8, 5
	s_lshl_b32 s8, s8, 8
	s_add_u32 s8, s8, 0x3648
	v_mov_b32_e32 v6, s8
	s_mov_b32 s8, 0
.Lfb_gp_2:
	global_load_dword v8, v6, s[4:5] sc1
	s_waitcnt vmcnt(0)
	v_cmp_le_u32_e32 vcc, 32, v8
	s_cbranch_vccnz .Lfb_gpd_2
	s_sleep 1
	s_add_u32 s8, s8, 1
	s_cmp_lt_u32 s8, 0x40000
	s_cbranch_scc1 .Lfb_gp_2

.Lfb_done_2:
	s_waitcnt vmcnt(0) lgkmcnt(0)
	v_mov_b32_e32 v6, 0x3e00
	v_mov_b32_e32 v7, 1
	global_atomic_add v6, v7, s[4:5]
	s_branch .LBB0_420
.Lfb_slow_2:
	s_add_u32 s4, s92, 0x510000
	s_addc_u32 s5, s93, 0
	v_mov_b32_e32 v6, 0x3e00
	v_mov_b32_e32 v7, 1
	global_atomic_add v6, v7, s[4:5]
	s_add_i32 s3, 0, 0x23ff0
	v_mov_b32_e32 v0, s3
	s_waitcnt vmcnt(0) expcnt(0) lgkmcnt(0)
	ds_read_b32 v2, v0
	s_add_i32 s3, 0, 0x23ff4
	v_mov_b32_e32 v0, s3
	ds_read_b32 v0, v0
	s_waitcnt lgkmcnt(1)
	v_cmp_ne_u32_e32 vcc, 0, v2
	s_cbranch_vccnz .LBB0_384
	s_mov_b32 s3, 1
	v_mov_b32_e32 v16, 0
	s_branch .LBB0_372
